# rw_phaseB rewritten barrier-free: each wave owns a 16-column v-block of the state for all d (k index permuted consistently in A/B so the bf16 image of its accumulators is the next MFMA B operand), 128
# speedup vs baseline: 1.0679x; 1.0162x over previous
; #define LAS __attribute__((address_space(3)))
; __device__ __forceinline__ unsigned cvt_pk_bf16(float lo, float hi) { const bf16x2_t r = __builtin_convertvector((f32x2){lo, hi}, bf16x2_t); return __builtin_bit_cast(unsigned, r); }
; #define LDS_BAR() do { asm volatile("s_waitcnt lgkmcnt(0)" ::: "memory"); __builtin_amdgcn_s_barrier(); asm volatile("" ::: "memory"); } while (0)
; __device__ __forceinline__ void rw_phaseA(LAS unsigned char* lds, const RwCtx& X, int item) {
;     ...
;     {
;         int tid = threadIdx.x; asm volatile("" : "+v"(tid));
;         const int wave = tid >> 6, lane = tid & 63, fr = lane & 15, fq = lane >> 4;
;         const int d0 = (wave >> 1) * 16;
;         bf16x8 fb[2], fk2[2];
; #pragma unroll
;         for (int k = 0; k < 2; ++k) { fb[k] = *(const LAS bf16x8*)(BtT + (d0 + fr) * 72 + k * 32 + fq * 8); fk2[k] = *(const LAS bf16x8*)(KtT + (d0 + fr) * 72 + k * 32 + fq * 8); }
; #pragma unroll
;         for (int bi = 0; bi < 2; ++bi) { const int n0 = ((wave & 1) * 2 + bi) * 16; f32x4 accp = (f32x4){0.f, 0.f, 0.f, 0.f}; f32x4 accr = accp;
; #pragma unroll
;             for (int k = 0; k < 2; ++k) { const bf16x8 fw = *(const LAS bf16x8*)(WT + (n0 + fr) * 72 + k * 32 + fq * 8), fu = *(const LAS bf16x8*)(UT + (n0 + fr) * 72 + k * 32 + fq * 8), fv = *(const LAS bf16x8*)(VT + (n0 + fr) * 72 + k * 32 + fq * 8);
;                 accp = __builtin_amdgcn_mfma_f32_16x16x32_bf16(fw, fb[k], accp, 0, 0, 0);
;                 accr = __builtin_amdgcn_mfma_f32_16x16x32_bf16(fb[k], fu, accr, 0, 0, 0);
;                 accr = __builtin_amdgcn_mfma_f32_16x16x32_bf16(fk2[k], fv, accr, 0, 0, 0); }
;             u32x2 op; op.x = cvt_pk_bf16(accp[0], accp[1]); op.y = cvt_pk_bf16(accp[2], accp[3]);
;             *(u32x2*)(gi + RWI_P + ((size_t)(d0 + fr) * 64 + n0 + fq * 4) * 2) = op;
;             u32x2 orr; orr.x = cvt_pk_bf16(accr[0], accr[1]); orr.y = cvt_pk_bf16(accr[2], accr[3]);
;             *(u32x2*)(gi + RWI_R + ((size_t)((wave * 2 + bi) * 64 + lane)) * 8) = orr; }
; #pragma unroll
;         for (int j = 0; j < 2; ++j) { const int q = tid + 512 * j; *(u32x4*)(gi + RWI_W + (size_t)q * 16) = *(const LAS u32x4*)(lds + (size_t)q * 16); }
;     }
;     LDS_BAR();
.LBB0_720:
	s_or_b64 exec, exec, s[0:1]
	v_mov_b32_e32 v0, v226
	s_waitcnt lgkmcnt(0)
	s_barrier
	s_add_i32 s27, s27, s94
	v_ashrrev_i32_e32 v40, 6, v0
	v_lshlrev_b32_e32 v4, 5, v40
	v_and_b32_e32 v1, 15, v0
	v_and_b32_e32 v41, 32, v4
	v_or_b32_e32 v1, v41, v1
	v_ashrrev_i32_e32 v2, 3, v0
	v_and_b32_e32 v3, 48, v0
	v_mul_u32_u24_e32 v4, 0x48, v1
	v_add_u32_e32 v8, 0, v3
	v_lshlrev_b32_e32 v18, 1, v4
	v_bfi_b32 v2, -16, v2, v0
	v_add_u32_e32 v42, v8, v18
	v_mad_u64_u32 v[34:35], s[0:1], v2, s91, v[8:9]
	v_add_u32_e32 v43, s8, v3
	ds_read_b128 v[4:7], v42 offset:18432
	ds_read_b128 v[10:13], v34 offset:27648
	ds_read_b128 v[14:17], v34 offset:36864
	v_add_u32_e32 v3, v43, v18
	ds_read_b128 v[18:21], v3
	ds_read_b128 v[22:25], v42 offset:46080
	ds_read_b128 v[26:29], v42 offset:18496
	s_waitcnt lgkmcnt(2)
	v_mfma_f32_16x16x32_bf16 v[18:21], v[10:13], v[18:21], 0
	ds_read_b128 v[30:33], v34 offset:27712
	v_or_b32_e32 v1, 16, v1
	v_mul_u32_u24_e32 v1, 0x48, v1
	s_waitcnt lgkmcnt(2)
	v_mfma_f32_16x16x32_bf16 v[18:21], v[14:17], v[22:25], v[18:21]
	ds_read_b128 v[22:25], v34 offset:36928
	ds_read_b128 v[34:37], v3 offset:64
	v_lshlrev_b32_e32 v1, 1, v1
	v_add_u32_e32 v8, v8, v1
	v_mfma_f32_16x16x32_bf16 v[4:7], v[4:7], v[10:13], 0
	v_and_b32_e32 v44, 63, v0
	v_bfe_u32 v45, v0, 4, 2
	v_add_u32_e32 v1, v43, v1
	s_waitcnt lgkmcnt(2)
	v_mfma_f32_16x16x32_bf16 v[4:7], v[26:29], v[30:33], v[4:7]
	v_lshlrev_b32_e32 v48, 4, v45
	ds_read_b128 v[26:29], v42 offset:46144
	v_lshlrev_b32_e32 v46, 3, v45
	s_waitcnt lgkmcnt(1)
	v_mfma_f32_16x16x32_bf16 v[18:21], v[30:33], v[34:37], v[18:21]
	ds_read_b128 v[34:37], v8 offset:18432
	v_lshl_or_b32 v42, v40, 7, v44
	s_nop 0
	v_cvt_pk_bf16_f32 v44, v4, v5
	v_cvt_pk_bf16_f32 v45, v6, v7
	ds_read_b128 v[4:7], v1
	v_ashrrev_i32_e32 v3, 31, v2
	v_lshlrev_b64 v[38:39], 6, v[2:3]
	v_or3_b32 v38, v38, v46, v41
	s_waitcnt lgkmcnt(2)
	v_mfma_f32_16x16x32_bf16 v[18:21], v[22:25], v[26:29], v[18:21]
	v_lshl_add_u64 v[46:47], v[38:39], 1, s[6:7]
	v_ashrrev_i32_e32 v43, 31, v42
	s_movk_i32 s0, 0x2000
	s_waitcnt lgkmcnt(1)
	v_mfma_f32_16x16x32_bf16 v[26:29], v[34:37], v[10:13], 0
	ds_read_b128 v[34:37], v8 offset:46080
	ds_read_b128 v[38:41], v8 offset:18496
	global_store_dwordx2 v[46:47], v[44:45], off
	v_cvt_pk_bf16_f32 v44, v18, v19
	s_waitcnt lgkmcnt(2)
	v_mfma_f32_16x16x32_bf16 v[4:7], v[10:13], v[4:7], 0
	ds_read_b128 v[10:13], v1 offset:64
	v_cvt_pk_bf16_f32 v45, v20, v21
	ds_read_b128 v[18:21], v8 offset:46144
	s_waitcnt lgkmcnt(3)
	v_mfma_f32_16x16x32_bf16 v[4:7], v[14:17], v[34:37], v[4:7]
	v_lshl_add_u64 v[34:35], v[42:43], 3, s[6:7]
	v_lshlrev_b64 v[2:3], 7, v[2:3]
	v_and_b32_e32 v1, 64, v0
	s_waitcnt lgkmcnt(1)
	v_mfma_f32_16x16x32_bf16 v[4:7], v[30:33], v[10:13], v[4:7]
	v_or3_b32 v2, v2, v1, v48
	v_lshl_add_u64 v[2:3], s[6:7], 0, v[2:3]
	v_ashrrev_i32_e32 v1, 31, v0
	v_mfma_f32_16x16x32_bf16 v[14:17], v[38:41], v[30:33], v[26:29]
	s_add_i32 s26, s26, s33
	s_movk_i32 s83, 0x2000
	s_waitcnt lgkmcnt(0)
	v_mfma_f32_16x16x32_bf16 v[4:7], v[22:25], v[18:21], v[4:7]
	v_add_co_u32_e32 v26, vcc, s0, v34
	s_nop 2
	v_cvt_pk_bf16_f32 v10, v14, v15
	v_addc_co_u32_e32 v27, vcc, 0, v35, vcc
	v_cvt_pk_bf16_f32 v11, v16, v17
	global_store_dwordx2 v[26:27], v[44:45], off
	global_store_dwordx2 v[2:3], v[10:11], off offset:8
	v_cvt_pk_bf16_f32 v2, v4, v5
	v_or_b32_e32 v4, 64, v42
	v_ashrrev_i32_e32 v5, 31, v4
	v_lshl_add_u64 v[4:5], v[4:5], 3, s[6:7]
	v_add_co_u32_e32 v4, vcc, s0, v4
	v_cvt_pk_bf16_f32 v3, v6, v7
	s_nop 0
	v_addc_co_u32_e32 v5, vcc, 0, v5, vcc
	global_store_dwordx2 v[4:5], v[2:3], off
	v_lshlrev_b64 v[4:5], 4, v[0:1]
	v_add_u32_e32 v0, 0, v4
	ds_read_b128 v[0:3], v0
	v_lshl_add_u64 v[6:7], s[6:7], 0, v[4:5]
	s_movk_i32 s0, 0x4000
	v_add_co_u32_e32 v6, vcc, s0, v6
	v_lshl_add_u64 v[4:5], v[4:5], 0, s[62:63]
	s_nop 0
	v_addc_co_u32_e32 v7, vcc, 0, v7, vcc
	s_waitcnt lgkmcnt(0)
	global_store_dwordx4 v[6:7], v[0:3], off offset:256
	s_nop 1
	v_add_u32_e32 v0, 0, v4
	ds_read_b128 v[0:3], v0
	v_lshl_add_u64 v[4:5], s[6:7], 0, v[4:5]
	v_add_co_u32_e32 v4, vcc, s0, v4
	s_mul_i32 s0, s20, 0x8100
	s_nop 0
	v_addc_co_u32_e32 v5, vcc, 0, v5, vcc
	s_waitcnt lgkmcnt(0)
	global_store_dwordx4 v[4:5], v[0:3], off offset:256
	s_waitcnt lgkmcnt(0)
	s_barrier
	s_add_u32 s6, s6, s0
	s_mul_hi_i32 s0, s20, 0x8100
	s_addc_u32 s7, s7, s0
	s_cmpk_gt_i32 s27, 0x101f
	s_cbranch_scc1 .LBB0_716

; #define LAS __attribute__((address_space(3)))
; __device__ __forceinline__ void rw_phaseB(LAS unsigned char* lds, const RwCtx& X, int bh) {
;     int tid = threadIdx.x; asm volatile("" : "+v"(tid));
;     const int wave = tid >> 6, lane = tid & 63, fr = lane & 15, fq = lane >> 4;
;     const int d0 = (wave >> 1) * 16, vb0 = (wave & 1) * 2;
;     f32x4 acc[2]; acc[0] = (f32x4){0.f, 0.f, 0.f, 0.f}; acc[1] = acc[0];
;     const unsigned char* gi = X.RWI + (size_t)bh * NCH * RWI_BYTES;
;     bf16x8 pa[4][2], pn[4][2]; u32x2 rf[4][2], rn[4][2]; f32x4 dc[4], dn[4];
;     ...
; #pragma unroll
;     for (int j = 0; j < 4; ++j) RWB_LOAD(pa[j], rf[j], dc[j], j);
.LBB0_1163:
	s_or_b64 exec, exec, s[6:7]
	v_readlane_b32 s0, v253, 42
	v_readlane_b32 s1, v253, 43
	s_and_b64 vcc, exec, s[0:1]
	s_sub_i32 s0, s94, 127
	s_cmp_lt_u32 s2, s0
	s_cbranch_scc1 .LBB0_1187
	v_lshrrev_b32_e32 v8, 6, v226
	v_and_b32_e32 v14, 15, v226
	v_readfirstlane_b32 s7, v8
	v_bfe_u32 v15, v226, 4, 2
	s_sub_i32 s6, s94, 127
	s_sub_i32 s6, s2, s6
	s_mul_i32 s8, s7, 127
	s_add_i32 s6, s6, s8
	s_cmp_gt_u32 s6, 127
	s_cbranch_scc1 .LBB0_1186
	s_lshr_b32 s7, s6, 2
	s_and_b32 s8, s6, 3
	s_add_u32 s0, s92, 0x6ff4a000
	s_addc_u32 s1, s93, 0
	s_mul_i32 s34, s7, 0x410100
	s_add_u32 s0, s0, s34
	s_addc_u32 s1, s1, 0
	s_mul_i32 s6, s7, 0x102000
	s_add_u32 s34, s92, 0x7814c000
	s_addc_u32 s35, s93, 0
	s_add_u32 s34, s34, s6
	s_addc_u32 s35, s35, 0
	v_mov_b32_e32 v41, 0
	v_lshlrev_b32_e32 v40, 7, v14
	v_lshl_add_u32 v40, v15, 4, v40
	v_lshl_add_u64 v[0:1], s[0:1], 0, v[40:41]
	s_mov_b64 s[100:101], 0x1000
	v_lshl_add_u64 v[2:3], v[0:1], 0, s[100:101]
	s_lshl_b32 s6, s8, 6
	v_and_b32_e32 v40, 63, v226
	v_add_u32_e32 v40, s6, v40
	v_lshlrev_b32_e32 v40, 3, v40
	v_add_u32_e32 v40, 0x2000, v40
	v_lshl_add_u64 v[4:5], s[0:1], 0, v[40:41]
	v_lshl_add_u64 v[6:7], v[4:5], 0, s[100:101]
	v_lshlrev_b32_e32 v40, 4, v15
	v_add_u32_e32 v40, 0x4000, v40
	v_lshl_add_u64 v[10:11], s[0:1], 0, v[40:41]
	s_lshl_b32 s6, s8, 4
	v_add_u32_e32 v40, s6, v14
	v_lshlrev_b32_e32 v40, 7, v40
	v_lshl_add_u32 v40, v15, 3, v40
	v_lshl_add_u64 v[12:13], s[34:35], 0, v[40:41]
	v_mov_b32_e32 v16, 0
	v_mov_b32_e32 v17, 0
	v_mov_b32_e32 v18, 0
	v_mov_b32_e32 v19, 0
	v_mov_b32_e32 v20, 0
	v_mov_b32_e32 v21, 0
	v_mov_b32_e32 v22, 0
	v_mov_b32_e32 v23, 0
	v_mov_b32_e32 v24, 0
	v_mov_b32_e32 v25, 0
	v_mov_b32_e32 v26, 0
	v_mov_b32_e32 v27, 0
	v_mov_b32_e32 v28, 0
	v_mov_b32_e32 v29, 0
	v_mov_b32_e32 v30, 0
	v_mov_b32_e32 v31, 0
	global_load_dwordx4 v[48:51], v[0:1], off offset:0
	global_load_dwordx4 v[52:55], v[0:1], off offset:64
	global_load_dwordx4 v[56:59], v[0:1], off offset:2048
	global_load_dwordx4 v[60:63], v[0:1], off offset:2112
	global_load_dwordx4 v[64:67], v[2:3], off offset:0
	global_load_dwordx4 v[68:71], v[2:3], off offset:64
	global_load_dwordx4 v[72:75], v[2:3], off offset:2048
	global_load_dwordx4 v[76:79], v[2:3], off offset:2112
	global_load_dwordx2 v[80:81], v[4:5], off offset:0
	global_load_dwordx2 v[82:83], v[4:5], off offset:2048
	global_load_dwordx2 v[84:85], v[6:7], off offset:0
	global_load_dwordx2 v[86:87], v[6:7], off offset:2048
	global_load_dwordx4 v[88:91], v[10:11], off offset:0
	global_load_dwordx4 v[92:95], v[10:11], off offset:64
	global_load_dwordx4 v[96:99], v[10:11], off offset:128
	global_load_dwordx4 v[100:103], v[10:11], off offset:192
	v_add_co_u32_e32 v0, vcc, 0x8100, v0
	s_nop 1
	v_addc_co_u32_e32 v1, vcc, 0, v1, vcc
	v_add_co_u32_e32 v2, vcc, 0x8100, v2
	s_nop 1
	v_addc_co_u32_e32 v3, vcc, 0, v3, vcc
	v_add_co_u32_e32 v4, vcc, 0x8100, v4
	s_nop 1
	v_addc_co_u32_e32 v5, vcc, 0, v5, vcc
	v_add_co_u32_e32 v6, vcc, 0x8100, v6
	s_nop 1
	v_addc_co_u32_e32 v7, vcc, 0, v7, vcc
	v_add_co_u32_e32 v10, vcc, 0x8100, v10
	s_nop 1
	v_addc_co_u32_e32 v11, vcc, 0, v11, vcc
	global_load_dwordx4 v[104:107], v[0:1], off offset:0
	global_load_dwordx4 v[108:111], v[0:1], off offset:64
	global_load_dwordx4 v[112:115], v[0:1], off offset:2048
	global_load_dwordx4 v[116:119], v[0:1], off offset:2112
	global_load_dwordx4 v[120:123], v[2:3], off offset:0
	global_load_dwordx4 v[124:127], v[2:3], off offset:64
	global_load_dwordx4 v[128:131], v[2:3], off offset:2048
	global_load_dwordx4 v[132:135], v[2:3], off offset:2112
	global_load_dwordx2 v[136:137], v[4:5], off offset:0
	global_load_dwordx2 v[138:139], v[4:5], off offset:2048
	global_load_dwordx2 v[140:141], v[6:7], off offset:0
	global_load_dwordx2 v[148:149], v[6:7], off offset:2048
	global_load_dwordx4 v[150:153], v[10:11], off offset:0
	global_load_dwordx4 v[154:157], v[10:11], off offset:64
	global_load_dwordx4 v[158:161], v[10:11], off offset:128
	global_load_dwordx4 v[162:165], v[10:11], off offset:192
	v_add_co_u32_e32 v0, vcc, 0x8100, v0
	s_nop 1
	v_addc_co_u32_e32 v1, vcc, 0, v1, vcc
	v_add_co_u32_e32 v2, vcc, 0x8100, v2
	s_nop 1
	v_addc_co_u32_e32 v3, vcc, 0, v3, vcc
	v_add_co_u32_e32 v4, vcc, 0x8100, v4
	s_nop 1
	v_addc_co_u32_e32 v5, vcc, 0, v5, vcc
	v_add_co_u32_e32 v6, vcc, 0x8100, v6
	s_nop 1
	v_addc_co_u32_e32 v7, vcc, 0, v7, vcc
	v_add_co_u32_e32 v10, vcc, 0x8100, v10
	s_nop 1
	v_addc_co_u32_e32 v11, vcc, 0, v11, vcc
	global_load_dwordx4 v[166:169], v[0:1], off offset:0
	global_load_dwordx4 v[170:173], v[0:1], off offset:64
	global_load_dwordx4 v[174:177], v[0:1], off offset:2048
	global_load_dwordx4 v[178:181], v[0:1], off offset:2112
	global_load_dwordx4 v[182:185], v[2:3], off offset:0
	global_load_dwordx4 v[186:189], v[2:3], off offset:64
	global_load_dwordx4 v[190:193], v[2:3], off offset:2048
	global_load_dwordx4 v[194:197], v[2:3], off offset:2112
	global_load_dwordx2 v[198:199], v[4:5], off offset:0
	global_load_dwordx2 v[200:201], v[4:5], off offset:2048
	global_load_dwordx2 v[202:203], v[6:7], off offset:0
	global_load_dwordx2 v[204:205], v[6:7], off offset:2048
	global_load_dwordx4 v[206:209], v[10:11], off offset:0
	global_load_dwordx4 v[210:213], v[10:11], off offset:64
	global_load_dwordx4 v[214:217], v[10:11], off offset:128
	global_load_dwordx4 v[218:221], v[10:11], off offset:192
	v_add_co_u32_e32 v0, vcc, 0x8100, v0
	s_nop 1
	v_addc_co_u32_e32 v1, vcc, 0, v1, vcc
	v_add_co_u32_e32 v2, vcc, 0x8100, v2
	s_nop 1
	v_addc_co_u32_e32 v3, vcc, 0, v3, vcc
	v_add_co_u32_e32 v4, vcc, 0x8100, v4
	s_nop 1
	v_addc_co_u32_e32 v5, vcc, 0, v5, vcc
	v_add_co_u32_e32 v6, vcc, 0x8100, v6
	s_nop 1
	v_addc_co_u32_e32 v7, vcc, 0, v7, vcc
	v_add_co_u32_e32 v10, vcc, 0x8100, v10
	s_nop 1
	v_addc_co_u32_e32 v11, vcc, 0, v11, vcc
	s_waitcnt vmcnt(32)
; #define LAS __attribute__((address_space(3)))
; __device__ __forceinline__ unsigned cvt_pk_bf16(float lo, float hi) { const bf16x2_t r = __builtin_convertvector((f32x2){lo, hi}, bf16x2_t); return __builtin_bit_cast(unsigned, r); }
; __device__ __forceinline__ float bflo(unsigned u) { return __uint_as_float(u << 16); }
; __device__ __forceinline__ float bfhi(unsigned u) { return __uint_as_float(u & 0xffff0000u); }
; #define LDS_BAR() do { asm volatile("s_waitcnt lgkmcnt(0)" ::: "memory"); __builtin_amdgcn_s_barrier(); asm volatile("" ::: "memory"); } while (0)
; __device__ __forceinline__ void rw_phaseB(LAS unsigned char* lds, const RwCtx& X, int bh) {
;     ...
;     for (int c0 = 0; c0 < NCH; c0 += 4) {
; #pragma unroll
;         for (int j = 0; j < 4; ++j) { const int cn = c0 + 4 + j;
;             if (cn < NCH) RWB_LOAD(pn[j], rn[j], dn[j], cn);
;             else { pn[j][0] = pa[j][0]; pn[j][1] = pa[j][1]; rn[j][0] = rf[j][0]; rn[j][1] = rf[j][1]; dn[j] = dc[j]; } }
; #pragma unroll
;         for (int j = 0; j < 4; ++j) { const int c = c0 + j;
;             if (c < NCH) {
;                 LAS bf16_t* STb = (LAS bf16_t*)(lds + (c & 1) * 9216);
;                 bf16_t* sg = X.SRW + ((size_t)bh * NCH + c) * 4096;
; #pragma unroll
;                 for (int bi = 0; bi < 2; ++bi) { const int v0 = (vb0 + bi) * 16; u32x2 o; o.x = cvt_pk_bf16(acc[bi][0], acc[bi][1]); o.y = cvt_pk_bf16(acc[bi][2], acc[bi][3]);
;                     *(LAS u32x2*)(STb + (v0 + fr) * 72 + d0 + fq * 4) = o; *(u32x2*)(sg + (v0 + fr) * 64 + d0 + fq * 4) = o; }
;                 LDS_BAR();
; #pragma unroll
;                 for (int bi = 0; bi < 2; ++bi) { const int v0 = (vb0 + bi) * 16;
;                     f32x4 n = (f32x4){dc[j][0] * acc[bi][0] + bflo(rf[j][bi].x), dc[j][1] * acc[bi][1] + bfhi(rf[j][bi].x), dc[j][2] * acc[bi][2] + bflo(rf[j][bi].y), dc[j][3] * acc[bi][3] + bfhi(rf[j][bi].y)};
; #pragma unroll
;                     for (int k = 0; k < 2; ++k) { const bf16x8 fs = *(const LAS bf16x8*)(STb + (v0 + fr) * 72 + k * 32 + fq * 8); n = __builtin_amdgcn_mfma_f32_16x16x32_bf16(pa[j][k], fs, n, 0, 0, 0); }
;                     acc[bi] = n; }
;             } }
; #pragma unroll
;         for (int j = 0; j < 4; ++j) { pa[j][0] = pn[j][0]; pa[j][1] = pn[j][1]; rf[j][0] = rn[j][0]; rf[j][1] = rn[j][1]; dc[j] = dn[j]; }
;     }
	v_cvt_pk_bf16_f32 v32, v16, v17
	v_cvt_pk_bf16_f32 v33, v18, v19
	v_cvt_pk_bf16_f32 v34, v20, v21
	v_cvt_pk_bf16_f32 v35, v22, v23
	v_cvt_pk_bf16_f32 v36, v24, v25
	v_cvt_pk_bf16_f32 v37, v26, v27
	v_cvt_pk_bf16_f32 v38, v28, v29
	v_cvt_pk_bf16_f32 v39, v30, v31
	global_store_dwordx2 v[12:13], v[32:33], off offset:0
	global_store_dwordx2 v[12:13], v[34:35], off offset:32
	global_store_dwordx2 v[12:13], v[36:37], off offset:64
	global_store_dwordx2 v[12:13], v[38:39], off offset:96
	v_lshlrev_b32_e32 v40, 16, v80
	v_and_b32_e32 v41, 0xffff0000, v80
	v_lshlrev_b32_e32 v42, 16, v81
	v_and_b32_e32 v43, 0xffff0000, v81
	v_pk_fma_f32 v[16:17], v[16:17], v[88:89], v[40:41]
	v_pk_fma_f32 v[18:19], v[18:19], v[90:91], v[42:43]
	v_lshlrev_b32_e32 v40, 16, v82
	v_and_b32_e32 v41, 0xffff0000, v82
	v_lshlrev_b32_e32 v42, 16, v83
	v_and_b32_e32 v43, 0xffff0000, v83
	v_pk_fma_f32 v[20:21], v[20:21], v[92:93], v[40:41]
	v_pk_fma_f32 v[22:23], v[22:23], v[94:95], v[42:43]
	v_lshlrev_b32_e32 v40, 16, v84
	v_and_b32_e32 v41, 0xffff0000, v84
	v_lshlrev_b32_e32 v42, 16, v85
	v_and_b32_e32 v43, 0xffff0000, v85
	v_pk_fma_f32 v[24:25], v[24:25], v[96:97], v[40:41]
	v_pk_fma_f32 v[26:27], v[26:27], v[98:99], v[42:43]
	v_lshlrev_b32_e32 v40, 16, v86
	v_and_b32_e32 v41, 0xffff0000, v86
	v_lshlrev_b32_e32 v42, 16, v87
	v_and_b32_e32 v43, 0xffff0000, v87
	v_pk_fma_f32 v[28:29], v[28:29], v[100:101], v[40:41]
	v_pk_fma_f32 v[30:31], v[30:31], v[102:103], v[42:43]
	v_add_co_u32_e32 v12, vcc, 0x2000, v12
	s_nop 1
	v_addc_co_u32_e32 v13, vcc, 0, v13, vcc
	v_mfma_f32_16x16x32_bf16 v[16:19], v[48:51], v[32:35], v[16:19]
	v_mfma_f32_16x16x32_bf16 v[20:23], v[56:59], v[32:35], v[20:23]
	v_mfma_f32_16x16x32_bf16 v[24:27], v[64:67], v[32:35], v[24:27]
	v_mfma_f32_16x16x32_bf16 v[28:31], v[72:75], v[32:35], v[28:31]
	v_mfma_f32_16x16x32_bf16 v[16:19], v[52:55], v[36:39], v[16:19]
	v_mfma_f32_16x16x32_bf16 v[20:23], v[60:63], v[36:39], v[20:23]
	v_mfma_f32_16x16x32_bf16 v[24:27], v[68:71], v[36:39], v[24:27]
	v_mfma_f32_16x16x32_bf16 v[28:31], v[76:79], v[36:39], v[28:31]
	global_load_dwordx4 v[48:51], v[0:1], off offset:0
	global_load_dwordx4 v[52:55], v[0:1], off offset:64
	global_load_dwordx4 v[56:59], v[0:1], off offset:2048
	global_load_dwordx4 v[60:63], v[0:1], off offset:2112
	global_load_dwordx4 v[64:67], v[2:3], off offset:0
	global_load_dwordx4 v[68:71], v[2:3], off offset:64
	global_load_dwordx4 v[72:75], v[2:3], off offset:2048
	global_load_dwordx4 v[76:79], v[2:3], off offset:2112
	global_load_dwordx2 v[80:81], v[4:5], off offset:0
	global_load_dwordx2 v[82:83], v[4:5], off offset:2048
	global_load_dwordx2 v[84:85], v[6:7], off offset:0
	global_load_dwordx2 v[86:87], v[6:7], off offset:2048
	global_load_dwordx4 v[88:91], v[10:11], off offset:0
	global_load_dwordx4 v[92:95], v[10:11], off offset:64
	global_load_dwordx4 v[96:99], v[10:11], off offset:128
	global_load_dwordx4 v[100:103], v[10:11], off offset:192
	v_add_co_u32_e32 v0, vcc, 0x8100, v0
	s_nop 1
	v_addc_co_u32_e32 v1, vcc, 0, v1, vcc
	v_add_co_u32_e32 v2, vcc, 0x8100, v2
	s_nop 1
	v_addc_co_u32_e32 v3, vcc, 0, v3, vcc
	v_add_co_u32_e32 v4, vcc, 0x8100, v4
	s_nop 1
	v_addc_co_u32_e32 v5, vcc, 0, v5, vcc
	v_add_co_u32_e32 v6, vcc, 0x8100, v6
	s_nop 1
	v_addc_co_u32_e32 v7, vcc, 0, v7, vcc
	v_add_co_u32_e32 v10, vcc, 0x8100, v10
	s_nop 1
	v_addc_co_u32_e32 v11, vcc, 0, v11, vcc
	s_waitcnt vmcnt(36)
	v_cvt_pk_bf16_f32 v32, v16, v17
	v_cvt_pk_bf16_f32 v33, v18, v19
	v_cvt_pk_bf16_f32 v34, v20, v21
	v_cvt_pk_bf16_f32 v35, v22, v23
	v_cvt_pk_bf16_f32 v36, v24, v25
	v_cvt_pk_bf16_f32 v37, v26, v27
	v_cvt_pk_bf16_f32 v38, v28, v29
	v_cvt_pk_bf16_f32 v39, v30, v31
	global_store_dwordx2 v[12:13], v[32:33], off offset:0
	global_store_dwordx2 v[12:13], v[34:35], off offset:32
	global_store_dwordx2 v[12:13], v[36:37], off offset:64
	global_store_dwordx2 v[12:13], v[38:39], off offset:96
	v_lshlrev_b32_e32 v40, 16, v136
	v_and_b32_e32 v41, 0xffff0000, v136
	v_lshlrev_b32_e32 v42, 16, v137
	v_and_b32_e32 v43, 0xffff0000, v137
	v_pk_fma_f32 v[16:17], v[16:17], v[150:151], v[40:41]
	v_pk_fma_f32 v[18:19], v[18:19], v[152:153], v[42:43]
	v_lshlrev_b32_e32 v40, 16, v138
	v_and_b32_e32 v41, 0xffff0000, v138
	v_lshlrev_b32_e32 v42, 16, v139
	v_and_b32_e32 v43, 0xffff0000, v139
	v_pk_fma_f32 v[20:21], v[20:21], v[154:155], v[40:41]
	v_pk_fma_f32 v[22:23], v[22:23], v[156:157], v[42:43]
	v_lshlrev_b32_e32 v40, 16, v140
	v_and_b32_e32 v41, 0xffff0000, v140
	v_lshlrev_b32_e32 v42, 16, v141
	v_and_b32_e32 v43, 0xffff0000, v141
	v_pk_fma_f32 v[24:25], v[24:25], v[158:159], v[40:41]
	v_pk_fma_f32 v[26:27], v[26:27], v[160:161], v[42:43]
	v_lshlrev_b32_e32 v40, 16, v148
	v_and_b32_e32 v41, 0xffff0000, v148
	v_lshlrev_b32_e32 v42, 16, v149
	v_and_b32_e32 v43, 0xffff0000, v149
	v_pk_fma_f32 v[28:29], v[28:29], v[162:163], v[40:41]
	v_pk_fma_f32 v[30:31], v[30:31], v[164:165], v[42:43]
	v_add_co_u32_e32 v12, vcc, 0x2000, v12
	s_nop 1
	v_addc_co_u32_e32 v13, vcc, 0, v13, vcc
	v_mfma_f32_16x16x32_bf16 v[16:19], v[104:107], v[32:35], v[16:19]
	v_mfma_f32_16x16x32_bf16 v[20:23], v[112:115], v[32:35], v[20:23]
	v_mfma_f32_16x16x32_bf16 v[24:27], v[120:123], v[32:35], v[24:27]
	v_mfma_f32_16x16x32_bf16 v[28:31], v[128:131], v[32:35], v[28:31]
	v_mfma_f32_16x16x32_bf16 v[16:19], v[108:111], v[36:39], v[16:19]
	v_mfma_f32_16x16x32_bf16 v[20:23], v[116:119], v[36:39], v[20:23]
	v_mfma_f32_16x16x32_bf16 v[24:27], v[124:127], v[36:39], v[24:27]
	v_mfma_f32_16x16x32_bf16 v[28:31], v[132:135], v[36:39], v[28:31]
	global_load_dwordx4 v[104:107], v[0:1], off offset:0
	global_load_dwordx4 v[108:111], v[0:1], off offset:64
	global_load_dwordx4 v[112:115], v[0:1], off offset:2048
	global_load_dwordx4 v[116:119], v[0:1], off offset:2112
	global_load_dwordx4 v[120:123], v[2:3], off offset:0
	global_load_dwordx4 v[124:127], v[2:3], off offset:64
	global_load_dwordx4 v[128:131], v[2:3], off offset:2048
	global_load_dwordx4 v[132:135], v[2:3], off offset:2112
	global_load_dwordx2 v[136:137], v[4:5], off offset:0
	global_load_dwordx2 v[138:139], v[4:5], off offset:2048
	global_load_dwordx2 v[140:141], v[6:7], off offset:0
	global_load_dwordx2 v[148:149], v[6:7], off offset:2048
	global_load_dwordx4 v[150:153], v[10:11], off offset:0
	global_load_dwordx4 v[154:157], v[10:11], off offset:64
	global_load_dwordx4 v[158:161], v[10:11], off offset:128
	global_load_dwordx4 v[162:165], v[10:11], off offset:192
	v_add_co_u32_e32 v0, vcc, 0x8100, v0
	s_nop 1
	v_addc_co_u32_e32 v1, vcc, 0, v1, vcc
	v_add_co_u32_e32 v2, vcc, 0x8100, v2
	s_nop 1
	v_addc_co_u32_e32 v3, vcc, 0, v3, vcc
	v_add_co_u32_e32 v4, vcc, 0x8100, v4
	s_nop 1
	v_addc_co_u32_e32 v5, vcc, 0, v5, vcc
	v_add_co_u32_e32 v6, vcc, 0x8100, v6
	s_nop 1
	v_addc_co_u32_e32 v7, vcc, 0, v7, vcc
	v_add_co_u32_e32 v10, vcc, 0x8100, v10
	s_nop 1
	v_addc_co_u32_e32 v11, vcc, 0, v11, vcc
	s_waitcnt vmcnt(40)
; #define LAS __attribute__((address_space(3)))
; __device__ __forceinline__ unsigned cvt_pk_bf16(float lo, float hi) { const bf16x2_t r = __builtin_convertvector((f32x2){lo, hi}, bf16x2_t); return __builtin_bit_cast(unsigned, r); }
; __device__ __forceinline__ float bflo(unsigned u) { return __uint_as_float(u << 16); }
; __device__ __forceinline__ float bfhi(unsigned u) { return __uint_as_float(u & 0xffff0000u); }
; #define LDS_BAR() do { asm volatile("s_waitcnt lgkmcnt(0)" ::: "memory"); __builtin_amdgcn_s_barrier(); asm volatile("" ::: "memory"); } while (0)
; __device__ __forceinline__ void rw_phaseB(LAS unsigned char* lds, const RwCtx& X, int bh) {
;     ...
;     for (int c0 = 0; c0 < NCH; c0 += 4) {
; #pragma unroll
;         for (int j = 0; j < 4; ++j) { const int cn = c0 + 4 + j;
;             if (cn < NCH) RWB_LOAD(pn[j], rn[j], dn[j], cn);
;             else { pn[j][0] = pa[j][0]; pn[j][1] = pa[j][1]; rn[j][0] = rf[j][0]; rn[j][1] = rf[j][1]; dn[j] = dc[j]; } }
; #pragma unroll
;         for (int j = 0; j < 4; ++j) { const int c = c0 + j;
;             if (c < NCH) {
;                 LAS bf16_t* STb = (LAS bf16_t*)(lds + (c & 1) * 9216);
;                 bf16_t* sg = X.SRW + ((size_t)bh * NCH + c) * 4096;
; #pragma unroll
;                 for (int bi = 0; bi < 2; ++bi) { const int v0 = (vb0 + bi) * 16; u32x2 o; o.x = cvt_pk_bf16(acc[bi][0], acc[bi][1]); o.y = cvt_pk_bf16(acc[bi][2], acc[bi][3]);
;                     *(LAS u32x2*)(STb + (v0 + fr) * 72 + d0 + fq * 4) = o; *(u32x2*)(sg + (v0 + fr) * 64 + d0 + fq * 4) = o; }
;                 LDS_BAR();
; #pragma unroll
;                 for (int bi = 0; bi < 2; ++bi) { const int v0 = (vb0 + bi) * 16;
;                     f32x4 n = (f32x4){dc[j][0] * acc[bi][0] + bflo(rf[j][bi].x), dc[j][1] * acc[bi][1] + bfhi(rf[j][bi].x), dc[j][2] * acc[bi][2] + bflo(rf[j][bi].y), dc[j][3] * acc[bi][3] + bfhi(rf[j][bi].y)};
; #pragma unroll
;                     for (int k = 0; k < 2; ++k) { const bf16x8 fs = *(const LAS bf16x8*)(STb + (v0 + fr) * 72 + k * 32 + fq * 8); n = __builtin_amdgcn_mfma_f32_16x16x32_bf16(pa[j][k], fs, n, 0, 0, 0); }
;                     acc[bi] = n; }
;             } }
; #pragma unroll
;         for (int j = 0; j < 4; ++j) { pa[j][0] = pn[j][0]; pa[j][1] = pn[j][1]; rf[j][0] = rn[j][0]; rf[j][1] = rn[j][1]; dc[j] = dn[j]; }
;     }
	v_cvt_pk_bf16_f32 v32, v16, v17
	v_cvt_pk_bf16_f32 v33, v18, v19
	v_cvt_pk_bf16_f32 v34, v20, v21
	v_cvt_pk_bf16_f32 v35, v22, v23
	v_cvt_pk_bf16_f32 v36, v24, v25
	v_cvt_pk_bf16_f32 v37, v26, v27
	v_cvt_pk_bf16_f32 v38, v28, v29
	v_cvt_pk_bf16_f32 v39, v30, v31
	global_store_dwordx2 v[12:13], v[32:33], off offset:0
	global_store_dwordx2 v[12:13], v[34:35], off offset:32
	global_store_dwordx2 v[12:13], v[36:37], off offset:64
	global_store_dwordx2 v[12:13], v[38:39], off offset:96
	v_lshlrev_b32_e32 v40, 16, v198
	v_and_b32_e32 v41, 0xffff0000, v198
	v_lshlrev_b32_e32 v42, 16, v199
	v_and_b32_e32 v43, 0xffff0000, v199
	v_pk_fma_f32 v[16:17], v[16:17], v[206:207], v[40:41]
	v_pk_fma_f32 v[18:19], v[18:19], v[208:209], v[42:43]
	v_lshlrev_b32_e32 v40, 16, v200
	v_and_b32_e32 v41, 0xffff0000, v200
	v_lshlrev_b32_e32 v42, 16, v201
	v_and_b32_e32 v43, 0xffff0000, v201
	v_pk_fma_f32 v[20:21], v[20:21], v[210:211], v[40:41]
	v_pk_fma_f32 v[22:23], v[22:23], v[212:213], v[42:43]
	v_lshlrev_b32_e32 v40, 16, v202
	v_and_b32_e32 v41, 0xffff0000, v202
	v_lshlrev_b32_e32 v42, 16, v203
	v_and_b32_e32 v43, 0xffff0000, v203
	v_pk_fma_f32 v[24:25], v[24:25], v[214:215], v[40:41]
	v_pk_fma_f32 v[26:27], v[26:27], v[216:217], v[42:43]
	v_lshlrev_b32_e32 v40, 16, v204
	v_and_b32_e32 v41, 0xffff0000, v204
	v_lshlrev_b32_e32 v42, 16, v205
	v_and_b32_e32 v43, 0xffff0000, v205
	v_pk_fma_f32 v[28:29], v[28:29], v[218:219], v[40:41]
	v_pk_fma_f32 v[30:31], v[30:31], v[220:221], v[42:43]
	v_add_co_u32_e32 v12, vcc, 0x2000, v12
	s_nop 1
	v_addc_co_u32_e32 v13, vcc, 0, v13, vcc
	v_mfma_f32_16x16x32_bf16 v[16:19], v[166:169], v[32:35], v[16:19]
	v_mfma_f32_16x16x32_bf16 v[20:23], v[174:177], v[32:35], v[20:23]
	v_mfma_f32_16x16x32_bf16 v[24:27], v[182:185], v[32:35], v[24:27]
	v_mfma_f32_16x16x32_bf16 v[28:31], v[190:193], v[32:35], v[28:31]
	v_mfma_f32_16x16x32_bf16 v[16:19], v[170:173], v[36:39], v[16:19]
	v_mfma_f32_16x16x32_bf16 v[20:23], v[178:181], v[36:39], v[20:23]
	v_mfma_f32_16x16x32_bf16 v[24:27], v[186:189], v[36:39], v[24:27]
	v_mfma_f32_16x16x32_bf16 v[28:31], v[194:197], v[36:39], v[28:31]
	global_load_dwordx4 v[166:169], v[0:1], off offset:0
	global_load_dwordx4 v[170:173], v[0:1], off offset:64
	global_load_dwordx4 v[174:177], v[0:1], off offset:2048
	global_load_dwordx4 v[178:181], v[0:1], off offset:2112
	global_load_dwordx4 v[182:185], v[2:3], off offset:0
	global_load_dwordx4 v[186:189], v[2:3], off offset:64
	global_load_dwordx4 v[190:193], v[2:3], off offset:2048
	global_load_dwordx4 v[194:197], v[2:3], off offset:2112
	global_load_dwordx2 v[198:199], v[4:5], off offset:0
	global_load_dwordx2 v[200:201], v[4:5], off offset:2048
	global_load_dwordx2 v[202:203], v[6:7], off offset:0
	global_load_dwordx2 v[204:205], v[6:7], off offset:2048
	global_load_dwordx4 v[206:209], v[10:11], off offset:0
	global_load_dwordx4 v[210:213], v[10:11], off offset:64
	global_load_dwordx4 v[214:217], v[10:11], off offset:128
	global_load_dwordx4 v[218:221], v[10:11], off offset:192
	v_add_co_u32_e32 v0, vcc, 0x8100, v0
	s_nop 1
	v_addc_co_u32_e32 v1, vcc, 0, v1, vcc
	v_add_co_u32_e32 v2, vcc, 0x8100, v2
	s_nop 1
	v_addc_co_u32_e32 v3, vcc, 0, v3, vcc
	v_add_co_u32_e32 v4, vcc, 0x8100, v4
	s_nop 1
	v_addc_co_u32_e32 v5, vcc, 0, v5, vcc
	v_add_co_u32_e32 v6, vcc, 0x8100, v6
	s_nop 1
	v_addc_co_u32_e32 v7, vcc, 0, v7, vcc
	v_add_co_u32_e32 v10, vcc, 0x8100, v10
	s_nop 1
	v_addc_co_u32_e32 v11, vcc, 0, v11, vcc
	s_mov_b32 s6, 41
.Lrwb_loop:
	s_waitcnt vmcnt(40)
	v_cvt_pk_bf16_f32 v32, v16, v17
	v_cvt_pk_bf16_f32 v33, v18, v19
	v_cvt_pk_bf16_f32 v34, v20, v21
	v_cvt_pk_bf16_f32 v35, v22, v23
	v_cvt_pk_bf16_f32 v36, v24, v25
	v_cvt_pk_bf16_f32 v37, v26, v27
	v_cvt_pk_bf16_f32 v38, v28, v29
	v_cvt_pk_bf16_f32 v39, v30, v31
	global_store_dwordx2 v[12:13], v[32:33], off offset:0
	global_store_dwordx2 v[12:13], v[34:35], off offset:32
	global_store_dwordx2 v[12:13], v[36:37], off offset:64
	global_store_dwordx2 v[12:13], v[38:39], off offset:96
	v_lshlrev_b32_e32 v40, 16, v80
	v_and_b32_e32 v41, 0xffff0000, v80
	v_lshlrev_b32_e32 v42, 16, v81
	v_and_b32_e32 v43, 0xffff0000, v81
	v_pk_fma_f32 v[16:17], v[16:17], v[88:89], v[40:41]
	v_pk_fma_f32 v[18:19], v[18:19], v[90:91], v[42:43]
	v_lshlrev_b32_e32 v40, 16, v82
	v_and_b32_e32 v41, 0xffff0000, v82
	v_lshlrev_b32_e32 v42, 16, v83
	v_and_b32_e32 v43, 0xffff0000, v83
	v_pk_fma_f32 v[20:21], v[20:21], v[92:93], v[40:41]
	v_pk_fma_f32 v[22:23], v[22:23], v[94:95], v[42:43]
	v_lshlrev_b32_e32 v40, 16, v84
	v_and_b32_e32 v41, 0xffff0000, v84
	v_lshlrev_b32_e32 v42, 16, v85
	v_and_b32_e32 v43, 0xffff0000, v85
	v_pk_fma_f32 v[24:25], v[24:25], v[96:97], v[40:41]
	v_pk_fma_f32 v[26:27], v[26:27], v[98:99], v[42:43]
	v_lshlrev_b32_e32 v40, 16, v86
	v_and_b32_e32 v41, 0xffff0000, v86
	v_lshlrev_b32_e32 v42, 16, v87
	v_and_b32_e32 v43, 0xffff0000, v87
	v_pk_fma_f32 v[28:29], v[28:29], v[100:101], v[40:41]
	v_pk_fma_f32 v[30:31], v[30:31], v[102:103], v[42:43]
	v_add_co_u32_e32 v12, vcc, 0x2000, v12
	s_nop 1
	v_addc_co_u32_e32 v13, vcc, 0, v13, vcc
	v_mfma_f32_16x16x32_bf16 v[16:19], v[48:51], v[32:35], v[16:19]
	v_mfma_f32_16x16x32_bf16 v[20:23], v[56:59], v[32:35], v[20:23]
	v_mfma_f32_16x16x32_bf16 v[24:27], v[64:67], v[32:35], v[24:27]
	v_mfma_f32_16x16x32_bf16 v[28:31], v[72:75], v[32:35], v[28:31]
	v_mfma_f32_16x16x32_bf16 v[16:19], v[52:55], v[36:39], v[16:19]
	v_mfma_f32_16x16x32_bf16 v[20:23], v[60:63], v[36:39], v[20:23]
	v_mfma_f32_16x16x32_bf16 v[24:27], v[68:71], v[36:39], v[24:27]
	v_mfma_f32_16x16x32_bf16 v[28:31], v[76:79], v[36:39], v[28:31]
	global_load_dwordx4 v[48:51], v[0:1], off offset:0
	global_load_dwordx4 v[52:55], v[0:1], off offset:64
	global_load_dwordx4 v[56:59], v[0:1], off offset:2048
	global_load_dwordx4 v[60:63], v[0:1], off offset:2112
	global_load_dwordx4 v[64:67], v[2:3], off offset:0
	global_load_dwordx4 v[68:71], v[2:3], off offset:64
	global_load_dwordx4 v[72:75], v[2:3], off offset:2048
	global_load_dwordx4 v[76:79], v[2:3], off offset:2112
	global_load_dwordx2 v[80:81], v[4:5], off offset:0
	global_load_dwordx2 v[82:83], v[4:5], off offset:2048
	global_load_dwordx2 v[84:85], v[6:7], off offset:0
	global_load_dwordx2 v[86:87], v[6:7], off offset:2048
	global_load_dwordx4 v[88:91], v[10:11], off offset:0
	global_load_dwordx4 v[92:95], v[10:11], off offset:64
	global_load_dwordx4 v[96:99], v[10:11], off offset:128
	global_load_dwordx4 v[100:103], v[10:11], off offset:192
	v_add_co_u32_e32 v0, vcc, 0x8100, v0
	s_nop 1
	v_addc_co_u32_e32 v1, vcc, 0, v1, vcc
	v_add_co_u32_e32 v2, vcc, 0x8100, v2
	s_nop 1
	v_addc_co_u32_e32 v3, vcc, 0, v3, vcc
	v_add_co_u32_e32 v4, vcc, 0x8100, v4
	s_nop 1
	v_addc_co_u32_e32 v5, vcc, 0, v5, vcc
	v_add_co_u32_e32 v6, vcc, 0x8100, v6
	s_nop 1
	v_addc_co_u32_e32 v7, vcc, 0, v7, vcc
	v_add_co_u32_e32 v10, vcc, 0x8100, v10
	s_nop 1
	v_addc_co_u32_e32 v11, vcc, 0, v11, vcc
	s_waitcnt vmcnt(40)
; #define LAS __attribute__((address_space(3)))
; __device__ __forceinline__ unsigned cvt_pk_bf16(float lo, float hi) { const bf16x2_t r = __builtin_convertvector((f32x2){lo, hi}, bf16x2_t); return __builtin_bit_cast(unsigned, r); }
; __device__ __forceinline__ float bflo(unsigned u) { return __uint_as_float(u << 16); }
; __device__ __forceinline__ float bfhi(unsigned u) { return __uint_as_float(u & 0xffff0000u); }
; #define LDS_BAR() do { asm volatile("s_waitcnt lgkmcnt(0)" ::: "memory"); __builtin_amdgcn_s_barrier(); asm volatile("" ::: "memory"); } while (0)
; __device__ __forceinline__ void rw_phaseB(LAS unsigned char* lds, const RwCtx& X, int bh) {
;     ...
;     for (int c0 = 0; c0 < NCH; c0 += 4) {
; #pragma unroll
;         for (int j = 0; j < 4; ++j) { const int cn = c0 + 4 + j;
;             if (cn < NCH) RWB_LOAD(pn[j], rn[j], dn[j], cn);
;             else { pn[j][0] = pa[j][0]; pn[j][1] = pa[j][1]; rn[j][0] = rf[j][0]; rn[j][1] = rf[j][1]; dn[j] = dc[j]; } }
; #pragma unroll
;         for (int j = 0; j < 4; ++j) { const int c = c0 + j;
;             if (c < NCH) {
;                 LAS bf16_t* STb = (LAS bf16_t*)(lds + (c & 1) * 9216);
;                 bf16_t* sg = X.SRW + ((size_t)bh * NCH + c) * 4096;
; #pragma unroll
;                 for (int bi = 0; bi < 2; ++bi) { const int v0 = (vb0 + bi) * 16; u32x2 o; o.x = cvt_pk_bf16(acc[bi][0], acc[bi][1]); o.y = cvt_pk_bf16(acc[bi][2], acc[bi][3]);
;                     *(LAS u32x2*)(STb + (v0 + fr) * 72 + d0 + fq * 4) = o; *(u32x2*)(sg + (v0 + fr) * 64 + d0 + fq * 4) = o; }
;                 LDS_BAR();
; #pragma unroll
;                 for (int bi = 0; bi < 2; ++bi) { const int v0 = (vb0 + bi) * 16;
;                     f32x4 n = (f32x4){dc[j][0] * acc[bi][0] + bflo(rf[j][bi].x), dc[j][1] * acc[bi][1] + bfhi(rf[j][bi].x), dc[j][2] * acc[bi][2] + bflo(rf[j][bi].y), dc[j][3] * acc[bi][3] + bfhi(rf[j][bi].y)};
; #pragma unroll
;                     for (int k = 0; k < 2; ++k) { const bf16x8 fs = *(const LAS bf16x8*)(STb + (v0 + fr) * 72 + k * 32 + fq * 8); n = __builtin_amdgcn_mfma_f32_16x16x32_bf16(pa[j][k], fs, n, 0, 0, 0); }
;                     acc[bi] = n; }
;             } }
; #pragma unroll
;         for (int j = 0; j < 4; ++j) { pa[j][0] = pn[j][0]; pa[j][1] = pn[j][1]; rf[j][0] = rn[j][0]; rf[j][1] = rn[j][1]; dc[j] = dn[j]; }
;     }
	v_cvt_pk_bf16_f32 v32, v16, v17
	v_cvt_pk_bf16_f32 v33, v18, v19
	v_cvt_pk_bf16_f32 v34, v20, v21
	v_cvt_pk_bf16_f32 v35, v22, v23
	v_cvt_pk_bf16_f32 v36, v24, v25
	v_cvt_pk_bf16_f32 v37, v26, v27
	v_cvt_pk_bf16_f32 v38, v28, v29
	v_cvt_pk_bf16_f32 v39, v30, v31
	global_store_dwordx2 v[12:13], v[32:33], off offset:0
	global_store_dwordx2 v[12:13], v[34:35], off offset:32
	global_store_dwordx2 v[12:13], v[36:37], off offset:64
	global_store_dwordx2 v[12:13], v[38:39], off offset:96
	v_lshlrev_b32_e32 v40, 16, v136
	v_and_b32_e32 v41, 0xffff0000, v136
	v_lshlrev_b32_e32 v42, 16, v137
	v_and_b32_e32 v43, 0xffff0000, v137
	v_pk_fma_f32 v[16:17], v[16:17], v[150:151], v[40:41]
	v_pk_fma_f32 v[18:19], v[18:19], v[152:153], v[42:43]
	v_lshlrev_b32_e32 v40, 16, v138
	v_and_b32_e32 v41, 0xffff0000, v138
	v_lshlrev_b32_e32 v42, 16, v139
	v_and_b32_e32 v43, 0xffff0000, v139
	v_pk_fma_f32 v[20:21], v[20:21], v[154:155], v[40:41]
	v_pk_fma_f32 v[22:23], v[22:23], v[156:157], v[42:43]
	v_lshlrev_b32_e32 v40, 16, v140
	v_and_b32_e32 v41, 0xffff0000, v140
	v_lshlrev_b32_e32 v42, 16, v141
	v_and_b32_e32 v43, 0xffff0000, v141
	v_pk_fma_f32 v[24:25], v[24:25], v[158:159], v[40:41]
	v_pk_fma_f32 v[26:27], v[26:27], v[160:161], v[42:43]
	v_lshlrev_b32_e32 v40, 16, v148
	v_and_b32_e32 v41, 0xffff0000, v148
	v_lshlrev_b32_e32 v42, 16, v149
	v_and_b32_e32 v43, 0xffff0000, v149
	v_pk_fma_f32 v[28:29], v[28:29], v[162:163], v[40:41]
	v_pk_fma_f32 v[30:31], v[30:31], v[164:165], v[42:43]
	v_add_co_u32_e32 v12, vcc, 0x2000, v12
	s_nop 1
	v_addc_co_u32_e32 v13, vcc, 0, v13, vcc
	v_mfma_f32_16x16x32_bf16 v[16:19], v[104:107], v[32:35], v[16:19]
	v_mfma_f32_16x16x32_bf16 v[20:23], v[112:115], v[32:35], v[20:23]
	v_mfma_f32_16x16x32_bf16 v[24:27], v[120:123], v[32:35], v[24:27]
	v_mfma_f32_16x16x32_bf16 v[28:31], v[128:131], v[32:35], v[28:31]
	v_mfma_f32_16x16x32_bf16 v[16:19], v[108:111], v[36:39], v[16:19]
	v_mfma_f32_16x16x32_bf16 v[20:23], v[116:119], v[36:39], v[20:23]
	v_mfma_f32_16x16x32_bf16 v[24:27], v[124:127], v[36:39], v[24:27]
	v_mfma_f32_16x16x32_bf16 v[28:31], v[132:135], v[36:39], v[28:31]
	global_load_dwordx4 v[104:107], v[0:1], off offset:0
	global_load_dwordx4 v[108:111], v[0:1], off offset:64
	global_load_dwordx4 v[112:115], v[0:1], off offset:2048
	global_load_dwordx4 v[116:119], v[0:1], off offset:2112
	global_load_dwordx4 v[120:123], v[2:3], off offset:0
	global_load_dwordx4 v[124:127], v[2:3], off offset:64
	global_load_dwordx4 v[128:131], v[2:3], off offset:2048
	global_load_dwordx4 v[132:135], v[2:3], off offset:2112
	global_load_dwordx2 v[136:137], v[4:5], off offset:0
	global_load_dwordx2 v[138:139], v[4:5], off offset:2048
	global_load_dwordx2 v[140:141], v[6:7], off offset:0
	global_load_dwordx2 v[148:149], v[6:7], off offset:2048
	global_load_dwordx4 v[150:153], v[10:11], off offset:0
	global_load_dwordx4 v[154:157], v[10:11], off offset:64
	global_load_dwordx4 v[158:161], v[10:11], off offset:128
	global_load_dwordx4 v[162:165], v[10:11], off offset:192
	v_add_co_u32_e32 v0, vcc, 0x8100, v0
	s_nop 1
	v_addc_co_u32_e32 v1, vcc, 0, v1, vcc
	v_add_co_u32_e32 v2, vcc, 0x8100, v2
	s_nop 1
	v_addc_co_u32_e32 v3, vcc, 0, v3, vcc
	v_add_co_u32_e32 v4, vcc, 0x8100, v4
	s_nop 1
	v_addc_co_u32_e32 v5, vcc, 0, v5, vcc
	v_add_co_u32_e32 v6, vcc, 0x8100, v6
	s_nop 1
	v_addc_co_u32_e32 v7, vcc, 0, v7, vcc
	v_add_co_u32_e32 v10, vcc, 0x8100, v10
	s_nop 1
	v_addc_co_u32_e32 v11, vcc, 0, v11, vcc
	s_waitcnt vmcnt(40)
	v_cvt_pk_bf16_f32 v32, v16, v17
	v_cvt_pk_bf16_f32 v33, v18, v19
	v_cvt_pk_bf16_f32 v34, v20, v21
	v_cvt_pk_bf16_f32 v35, v22, v23
	v_cvt_pk_bf16_f32 v36, v24, v25
	v_cvt_pk_bf16_f32 v37, v26, v27
	v_cvt_pk_bf16_f32 v38, v28, v29
	v_cvt_pk_bf16_f32 v39, v30, v31
	global_store_dwordx2 v[12:13], v[32:33], off offset:0
	global_store_dwordx2 v[12:13], v[34:35], off offset:32
	global_store_dwordx2 v[12:13], v[36:37], off offset:64
	global_store_dwordx2 v[12:13], v[38:39], off offset:96
	v_lshlrev_b32_e32 v40, 16, v198
	v_and_b32_e32 v41, 0xffff0000, v198
	v_lshlrev_b32_e32 v42, 16, v199
	v_and_b32_e32 v43, 0xffff0000, v199
	v_pk_fma_f32 v[16:17], v[16:17], v[206:207], v[40:41]
	v_pk_fma_f32 v[18:19], v[18:19], v[208:209], v[42:43]
	v_lshlrev_b32_e32 v40, 16, v200
	v_and_b32_e32 v41, 0xffff0000, v200
	v_lshlrev_b32_e32 v42, 16, v201
	v_and_b32_e32 v43, 0xffff0000, v201
	v_pk_fma_f32 v[20:21], v[20:21], v[210:211], v[40:41]
	v_pk_fma_f32 v[22:23], v[22:23], v[212:213], v[42:43]
	v_lshlrev_b32_e32 v40, 16, v202
	v_and_b32_e32 v41, 0xffff0000, v202
	v_lshlrev_b32_e32 v42, 16, v203
	v_and_b32_e32 v43, 0xffff0000, v203
	v_pk_fma_f32 v[24:25], v[24:25], v[214:215], v[40:41]
	v_pk_fma_f32 v[26:27], v[26:27], v[216:217], v[42:43]
	v_lshlrev_b32_e32 v40, 16, v204
	v_and_b32_e32 v41, 0xffff0000, v204
	v_lshlrev_b32_e32 v42, 16, v205
	v_and_b32_e32 v43, 0xffff0000, v205
	v_pk_fma_f32 v[28:29], v[28:29], v[218:219], v[40:41]
	v_pk_fma_f32 v[30:31], v[30:31], v[220:221], v[42:43]
	v_add_co_u32_e32 v12, vcc, 0x2000, v12
	s_nop 1
	v_addc_co_u32_e32 v13, vcc, 0, v13, vcc
	v_mfma_f32_16x16x32_bf16 v[16:19], v[166:169], v[32:35], v[16:19]
	v_mfma_f32_16x16x32_bf16 v[20:23], v[174:177], v[32:35], v[20:23]
	v_mfma_f32_16x16x32_bf16 v[24:27], v[182:185], v[32:35], v[24:27]
	v_mfma_f32_16x16x32_bf16 v[28:31], v[190:193], v[32:35], v[28:31]
	v_mfma_f32_16x16x32_bf16 v[16:19], v[170:173], v[36:39], v[16:19]
	v_mfma_f32_16x16x32_bf16 v[20:23], v[178:181], v[36:39], v[20:23]
	v_mfma_f32_16x16x32_bf16 v[24:27], v[186:189], v[36:39], v[24:27]
	v_mfma_f32_16x16x32_bf16 v[28:31], v[194:197], v[36:39], v[28:31]
	global_load_dwordx4 v[166:169], v[0:1], off offset:0
	global_load_dwordx4 v[170:173], v[0:1], off offset:64
	global_load_dwordx4 v[174:177], v[0:1], off offset:2048
	global_load_dwordx4 v[178:181], v[0:1], off offset:2112
	global_load_dwordx4 v[182:185], v[2:3], off offset:0
	global_load_dwordx4 v[186:189], v[2:3], off offset:64
	global_load_dwordx4 v[190:193], v[2:3], off offset:2048
	global_load_dwordx4 v[194:197], v[2:3], off offset:2112
	global_load_dwordx2 v[198:199], v[4:5], off offset:0
	global_load_dwordx2 v[200:201], v[4:5], off offset:2048
	global_load_dwordx2 v[202:203], v[6:7], off offset:0
	global_load_dwordx2 v[204:205], v[6:7], off offset:2048
	global_load_dwordx4 v[206:209], v[10:11], off offset:0
	global_load_dwordx4 v[210:213], v[10:11], off offset:64
	global_load_dwordx4 v[214:217], v[10:11], off offset:128
	global_load_dwordx4 v[218:221], v[10:11], off offset:192
	v_add_co_u32_e32 v0, vcc, 0x8100, v0
	s_nop 1
	v_addc_co_u32_e32 v1, vcc, 0, v1, vcc
	v_add_co_u32_e32 v2, vcc, 0x8100, v2
	s_nop 1
	v_addc_co_u32_e32 v3, vcc, 0, v3, vcc
	v_add_co_u32_e32 v4, vcc, 0x8100, v4
	s_nop 1
	v_addc_co_u32_e32 v5, vcc, 0, v5, vcc
	v_add_co_u32_e32 v6, vcc, 0x8100, v6
	s_nop 1
	v_addc_co_u32_e32 v7, vcc, 0, v7, vcc
	v_add_co_u32_e32 v10, vcc, 0x8100, v10
	s_nop 1
	v_addc_co_u32_e32 v11, vcc, 0, v11, vcc
	s_sub_i32 s6, s6, 1
	s_cmp_lg_u32 s6, 0
	s_cbranch_scc1 .Lrwb_loop
; #define LAS __attribute__((address_space(3)))
; __device__ __forceinline__ unsigned cvt_pk_bf16(float lo, float hi) { const bf16x2_t r = __builtin_convertvector((f32x2){lo, hi}, bf16x2_t); return __builtin_bit_cast(unsigned, r); }
; __device__ __forceinline__ float bflo(unsigned u) { return __uint_as_float(u << 16); }
; __device__ __forceinline__ float bfhi(unsigned u) { return __uint_as_float(u & 0xffff0000u); }
; #define LDS_BAR() do { asm volatile("s_waitcnt lgkmcnt(0)" ::: "memory"); __builtin_amdgcn_s_barrier(); asm volatile("" ::: "memory"); } while (0)
; __device__ __forceinline__ void rw_phaseB(LAS unsigned char* lds, const RwCtx& X, int bh) {
;     ...
;     for (int c0 = 0; c0 < NCH; c0 += 4) {
; #pragma unroll
;         for (int j = 0; j < 4; ++j) { const int cn = c0 + 4 + j;
;             if (cn < NCH) RWB_LOAD(pn[j], rn[j], dn[j], cn);
;             else { pn[j][0] = pa[j][0]; pn[j][1] = pa[j][1]; rn[j][0] = rf[j][0]; rn[j][1] = rf[j][1]; dn[j] = dc[j]; } }
; #pragma unroll
;         for (int j = 0; j < 4; ++j) { const int c = c0 + j;
;             if (c < NCH) {
;                 LAS bf16_t* STb = (LAS bf16_t*)(lds + (c & 1) * 9216);
;                 bf16_t* sg = X.SRW + ((size_t)bh * NCH + c) * 4096;
; #pragma unroll
;                 for (int bi = 0; bi < 2; ++bi) { const int v0 = (vb0 + bi) * 16; u32x2 o; o.x = cvt_pk_bf16(acc[bi][0], acc[bi][1]); o.y = cvt_pk_bf16(acc[bi][2], acc[bi][3]);
;                     *(LAS u32x2*)(STb + (v0 + fr) * 72 + d0 + fq * 4) = o; *(u32x2*)(sg + (v0 + fr) * 64 + d0 + fq * 4) = o; }
;                 LDS_BAR();
; #pragma unroll
;                 for (int bi = 0; bi < 2; ++bi) { const int v0 = (vb0 + bi) * 16;
;                     f32x4 n = (f32x4){dc[j][0] * acc[bi][0] + bflo(rf[j][bi].x), dc[j][1] * acc[bi][1] + bfhi(rf[j][bi].x), dc[j][2] * acc[bi][2] + bflo(rf[j][bi].y), dc[j][3] * acc[bi][3] + bfhi(rf[j][bi].y)};
; #pragma unroll
;                     for (int k = 0; k < 2; ++k) { const bf16x8 fs = *(const LAS bf16x8*)(STb + (v0 + fr) * 72 + k * 32 + fq * 8); n = __builtin_amdgcn_mfma_f32_16x16x32_bf16(pa[j][k], fs, n, 0, 0, 0); }
;                     acc[bi] = n; }
;             } }
; #pragma unroll
;         for (int j = 0; j < 4; ++j) { pa[j][0] = pn[j][0]; pa[j][1] = pn[j][1]; rf[j][0] = rn[j][0]; rf[j][1] = rn[j][1]; dc[j] = dn[j]; }
;     }
;     ...
;     LDS_BAR();
	s_waitcnt vmcnt(40)
	v_cvt_pk_bf16_f32 v32, v16, v17
	v_cvt_pk_bf16_f32 v33, v18, v19
	v_cvt_pk_bf16_f32 v34, v20, v21
	v_cvt_pk_bf16_f32 v35, v22, v23
	v_cvt_pk_bf16_f32 v36, v24, v25
	v_cvt_pk_bf16_f32 v37, v26, v27
	v_cvt_pk_bf16_f32 v38, v28, v29
	v_cvt_pk_bf16_f32 v39, v30, v31
	global_store_dwordx2 v[12:13], v[32:33], off offset:0
	global_store_dwordx2 v[12:13], v[34:35], off offset:32
	global_store_dwordx2 v[12:13], v[36:37], off offset:64
	global_store_dwordx2 v[12:13], v[38:39], off offset:96
	v_lshlrev_b32_e32 v40, 16, v80
	v_and_b32_e32 v41, 0xffff0000, v80
	v_lshlrev_b32_e32 v42, 16, v81
	v_and_b32_e32 v43, 0xffff0000, v81
	v_pk_fma_f32 v[16:17], v[16:17], v[88:89], v[40:41]
	v_pk_fma_f32 v[18:19], v[18:19], v[90:91], v[42:43]
	v_lshlrev_b32_e32 v40, 16, v82
	v_and_b32_e32 v41, 0xffff0000, v82
	v_lshlrev_b32_e32 v42, 16, v83
	v_and_b32_e32 v43, 0xffff0000, v83
	v_pk_fma_f32 v[20:21], v[20:21], v[92:93], v[40:41]
	v_pk_fma_f32 v[22:23], v[22:23], v[94:95], v[42:43]
	v_lshlrev_b32_e32 v40, 16, v84
	v_and_b32_e32 v41, 0xffff0000, v84
	v_lshlrev_b32_e32 v42, 16, v85
	v_and_b32_e32 v43, 0xffff0000, v85
	v_pk_fma_f32 v[24:25], v[24:25], v[96:97], v[40:41]
	v_pk_fma_f32 v[26:27], v[26:27], v[98:99], v[42:43]
	v_lshlrev_b32_e32 v40, 16, v86
	v_and_b32_e32 v41, 0xffff0000, v86
	v_lshlrev_b32_e32 v42, 16, v87
	v_and_b32_e32 v43, 0xffff0000, v87
	v_pk_fma_f32 v[28:29], v[28:29], v[100:101], v[40:41]
	v_pk_fma_f32 v[30:31], v[30:31], v[102:103], v[42:43]
	v_add_co_u32_e32 v12, vcc, 0x2000, v12
	s_nop 1
	v_addc_co_u32_e32 v13, vcc, 0, v13, vcc
	v_mfma_f32_16x16x32_bf16 v[16:19], v[48:51], v[32:35], v[16:19]
	v_mfma_f32_16x16x32_bf16 v[20:23], v[56:59], v[32:35], v[20:23]
	v_mfma_f32_16x16x32_bf16 v[24:27], v[64:67], v[32:35], v[24:27]
	v_mfma_f32_16x16x32_bf16 v[28:31], v[72:75], v[32:35], v[28:31]
	v_mfma_f32_16x16x32_bf16 v[16:19], v[52:55], v[36:39], v[16:19]
	v_mfma_f32_16x16x32_bf16 v[20:23], v[60:63], v[36:39], v[20:23]
	v_mfma_f32_16x16x32_bf16 v[24:27], v[68:71], v[36:39], v[24:27]
	v_mfma_f32_16x16x32_bf16 v[28:31], v[76:79], v[36:39], v[28:31]
	s_nop 7
	s_waitcnt vmcnt(24)
	v_cvt_pk_bf16_f32 v32, v16, v17
	v_cvt_pk_bf16_f32 v33, v18, v19
	v_cvt_pk_bf16_f32 v34, v20, v21
	v_cvt_pk_bf16_f32 v35, v22, v23
	v_cvt_pk_bf16_f32 v36, v24, v25
	v_cvt_pk_bf16_f32 v37, v26, v27
	v_cvt_pk_bf16_f32 v38, v28, v29
	v_cvt_pk_bf16_f32 v39, v30, v31
	global_store_dwordx2 v[12:13], v[32:33], off offset:0
	global_store_dwordx2 v[12:13], v[34:35], off offset:32
	global_store_dwordx2 v[12:13], v[36:37], off offset:64
	global_store_dwordx2 v[12:13], v[38:39], off offset:96
	v_lshlrev_b32_e32 v40, 16, v136
	v_and_b32_e32 v41, 0xffff0000, v136
	v_lshlrev_b32_e32 v42, 16, v137
	v_and_b32_e32 v43, 0xffff0000, v137
	v_pk_fma_f32 v[16:17], v[16:17], v[150:151], v[40:41]
	v_pk_fma_f32 v[18:19], v[18:19], v[152:153], v[42:43]
	v_lshlrev_b32_e32 v40, 16, v138
	v_and_b32_e32 v41, 0xffff0000, v138
	v_lshlrev_b32_e32 v42, 16, v139
	v_and_b32_e32 v43, 0xffff0000, v139
	v_pk_fma_f32 v[20:21], v[20:21], v[154:155], v[40:41]
	v_pk_fma_f32 v[22:23], v[22:23], v[156:157], v[42:43]
	v_lshlrev_b32_e32 v40, 16, v140
	v_and_b32_e32 v41, 0xffff0000, v140
	v_lshlrev_b32_e32 v42, 16, v141
	v_and_b32_e32 v43, 0xffff0000, v141
	v_pk_fma_f32 v[24:25], v[24:25], v[158:159], v[40:41]
	v_pk_fma_f32 v[26:27], v[26:27], v[160:161], v[42:43]
	v_lshlrev_b32_e32 v40, 16, v148
	v_and_b32_e32 v41, 0xffff0000, v148
	v_lshlrev_b32_e32 v42, 16, v149
	v_and_b32_e32 v43, 0xffff0000, v149
	v_pk_fma_f32 v[28:29], v[28:29], v[162:163], v[40:41]
	v_pk_fma_f32 v[30:31], v[30:31], v[164:165], v[42:43]
	v_add_co_u32_e32 v12, vcc, 0x2000, v12
	s_nop 1
	v_addc_co_u32_e32 v13, vcc, 0, v13, vcc
	v_mfma_f32_16x16x32_bf16 v[16:19], v[104:107], v[32:35], v[16:19]
	v_mfma_f32_16x16x32_bf16 v[20:23], v[112:115], v[32:35], v[20:23]
	v_mfma_f32_16x16x32_bf16 v[24:27], v[120:123], v[32:35], v[24:27]
	v_mfma_f32_16x16x32_bf16 v[28:31], v[128:131], v[32:35], v[28:31]
	v_mfma_f32_16x16x32_bf16 v[16:19], v[108:111], v[36:39], v[16:19]
	v_mfma_f32_16x16x32_bf16 v[20:23], v[116:119], v[36:39], v[20:23]
	v_mfma_f32_16x16x32_bf16 v[24:27], v[124:127], v[36:39], v[24:27]
	v_mfma_f32_16x16x32_bf16 v[28:31], v[132:135], v[36:39], v[28:31]
	s_nop 7
	s_waitcnt vmcnt(8)
	v_cvt_pk_bf16_f32 v32, v16, v17
	v_cvt_pk_bf16_f32 v33, v18, v19
	v_cvt_pk_bf16_f32 v34, v20, v21
	v_cvt_pk_bf16_f32 v35, v22, v23
	v_cvt_pk_bf16_f32 v36, v24, v25
	v_cvt_pk_bf16_f32 v37, v26, v27
	v_cvt_pk_bf16_f32 v38, v28, v29
	v_cvt_pk_bf16_f32 v39, v30, v31
	global_store_dwordx2 v[12:13], v[32:33], off offset:0
	global_store_dwordx2 v[12:13], v[34:35], off offset:32
	global_store_dwordx2 v[12:13], v[36:37], off offset:64
	global_store_dwordx2 v[12:13], v[38:39], off offset:96
	v_lshlrev_b32_e32 v40, 16, v198
	v_and_b32_e32 v41, 0xffff0000, v198
	v_lshlrev_b32_e32 v42, 16, v199
	v_and_b32_e32 v43, 0xffff0000, v199
	v_pk_fma_f32 v[16:17], v[16:17], v[206:207], v[40:41]
	v_pk_fma_f32 v[18:19], v[18:19], v[208:209], v[42:43]
	v_lshlrev_b32_e32 v40, 16, v200
	v_and_b32_e32 v41, 0xffff0000, v200
	v_lshlrev_b32_e32 v42, 16, v201
	v_and_b32_e32 v43, 0xffff0000, v201
	v_pk_fma_f32 v[20:21], v[20:21], v[210:211], v[40:41]
	v_pk_fma_f32 v[22:23], v[22:23], v[212:213], v[42:43]
	v_lshlrev_b32_e32 v40, 16, v202
	v_and_b32_e32 v41, 0xffff0000, v202
	v_lshlrev_b32_e32 v42, 16, v203
	v_and_b32_e32 v43, 0xffff0000, v203
	v_pk_fma_f32 v[24:25], v[24:25], v[214:215], v[40:41]
	v_pk_fma_f32 v[26:27], v[26:27], v[216:217], v[42:43]
	v_lshlrev_b32_e32 v40, 16, v204
	v_and_b32_e32 v41, 0xffff0000, v204
	v_lshlrev_b32_e32 v42, 16, v205
	v_and_b32_e32 v43, 0xffff0000, v205
	v_pk_fma_f32 v[28:29], v[28:29], v[218:219], v[40:41]
	v_pk_fma_f32 v[30:31], v[30:31], v[220:221], v[42:43]
	v_add_co_u32_e32 v12, vcc, 0x2000, v12
	s_nop 1
	v_addc_co_u32_e32 v13, vcc, 0, v13, vcc
	v_mfma_f32_16x16x32_bf16 v[16:19], v[166:169], v[32:35], v[16:19]
	v_mfma_f32_16x16x32_bf16 v[20:23], v[174:177], v[32:35], v[20:23]
	v_mfma_f32_16x16x32_bf16 v[24:27], v[182:185], v[32:35], v[24:27]
	v_mfma_f32_16x16x32_bf16 v[28:31], v[190:193], v[32:35], v[28:31]
	v_mfma_f32_16x16x32_bf16 v[16:19], v[170:173], v[36:39], v[16:19]
	v_mfma_f32_16x16x32_bf16 v[20:23], v[178:181], v[36:39], v[20:23]
	v_mfma_f32_16x16x32_bf16 v[24:27], v[186:189], v[36:39], v[24:27]
	v_mfma_f32_16x16x32_bf16 v[28:31], v[194:197], v[36:39], v[28:31]
	s_nop 7
	s_mov_b64 s[34:35], 0x8000
